# out-proj 128x128 tiles (the XCD-mapped path that runs): K block-granular through the 4-slot ring with three blocks in flight instead of one pair with vmcnt(0), rotated, DMA between MFMAs
# speedup vs baseline: 1.0089x; 1.0089x over previous
; DI int otid() { int t = threadIdx.x; asm volatile("" : "+v"(t)); return t; }
; template <bool VMODE, int TJ>
; DI void gemm_mainloop(const bf16_t* __restrict__ W, const bf16_t* __restrict__ X, int NW, char* smem, f32x16 (&acc)[2][TJ]) {
;     constexpr int XROWS = 64 * TJ, STAGE = (128 + XROWS) * 64, NPW = 2 + TJ;
;     const int tid = otid(), lane = tid & 63, wave = tid >> 6, r = lane & 31, h = lane >> 5, wf = wave & 1, wt = wave >> 1;
;     const int goff = (16 * wave + (lane >> 2)) * 32 + (((lane & 3) ^ (lane >> 4)) << 3);
;     const bf16_t* wp = W + goff;
;     const bf16_t* xp = X + goff;
;     const size_t wks = (size_t)NW * 32, xks = (size_t)NTOK * 32;
;     char* ld = smem + tid * 16;
;     ...
;     const int xr = (r >> 2) & 3;
;     const int fo0 = r * 64 + (((0 + h) ^ xr) << 4), fo1 = r * 64 + (((2 + h) ^ xr) << 4);
;     __syncthreads();
;     ...
;     if (TJ <= 2) {
;         constexpr int NSL = (TJ == 1) ? 6 : 4;
;         G_ISSUE(0, 0);
;         G_ISSUE(1, 1);
;         if (TJ == 1) { G_ISSUE(2, 2); G_ISSUE(3, 3); }
;         int sl = 0;
;         for (int kp = 0; kp < 16; ++kp) {
;             if (TJ == 1 && kp + 1 < 16) asm volatile("s_waitcnt vmcnt(6)" ::: "memory");
;             else asm volatile("s_waitcnt vmcnt(0)" ::: "memory");
;             __builtin_amdgcn_s_barrier();
;             const int sn2 = (TJ == 1) ? ((sl + 4 >= NSL) ? sl + 4 - NSL : sl + 4) : 2 - sl;
;             {
;                 const char* sw = smem + sl * STAGE + wf * 64 * 64;
;                 const char* sx = smem + sl * STAGE + 8192 + wt * (32 * TJ) * 64;
;                 bf16x8 fw[2], fx[TJ];
; #pragma unroll
;                 for (int i = 0; i < 2; ++i) fw[i] = *(const bf16x8*)(sw + i * 32 * 64 + fo0);
; #pragma unroll
;                 for (int j = 0; j < TJ; ++j) fx[j] = *(const bf16x8*)(sx + j * 32 * 64 + fo0);
;                 __builtin_amdgcn_sched_barrier(0);
;                 if (TJ == 1) { if (kp + 2 < 16) { G_ISSUE(2 * kp + 4, sn2); G_ISSUE(2 * kp + 5, sn2 + 1); } }
;                 else if (kp + 1 < 16) { G_ISSUE(2 * kp + 2, sn2); G_ISSUE(2 * kp + 3, sn2 + 1); }
;                 __builtin_amdgcn_sched_barrier(0);
.LBB0_39:
	v_mov_b32_e32 v116, v200
	s_load_dwordx2 s[8:9], s[0:1], 0xd8
	s_load_dwordx2 s[56:57], s[0:1], 0xb8
	s_xor_b64 s[62:63], s[4:5], -1
	v_readlane_b32 s4, v254, 13
	v_mov_b32_e32 v8, v200
	s_add_i32 s4, s6, s4
	s_and_b32 s28, s4, 0x7fffff80
	v_bfe_u32 v1, v8, 4, 2
	v_bitop3_b32 v1, v1, v8, 3 bitop3:0x78
	s_waitcnt lgkmcnt(0)
	s_add_u32 s8, s8, s58
	v_lshlrev_b32_e32 v0, 3, v8
	v_lshlrev_b32_e32 v1, 3, v1
	s_movk_i32 s29, 0xffe0
	s_addc_u32 s9, s9, s59
	v_readlane_b32 s4, v254, 14
	v_and_or_b32 v0, v0, s29, v1
	s_add_u32 s4, s8, s4
	v_ashrrev_i32_e32 v1, 31, v0
	v_lshl_add_u32 v66, v8, 4, 32
	s_addc_u32 s5, s9, 0
	v_readlane_b32 s6, v255, 23
	v_lshlrev_b64 v[64:65], 1, v[0:1]
	v_readfirstlane_b32 s29, v66
	v_add_u32_e32 v6, 0x1000, v66
	s_add_i32 s6, s6, s28
	s_mov_b32 s7, s75
	v_lshl_add_u64 v[0:1], s[4:5], 0, v[64:65]
	s_mov_b32 m0, s29
	v_readfirstlane_b32 s29, v6
	s_lshl_b64 s[6:7], s[6:7], 6
	s_barrier
	global_load_lds_dwordx4 v[0:1], off
	v_lshl_add_u64 v[4:5], v[0:1], 0, s[26:27]
	s_mov_b32 m0, s29
	s_add_u32 s6, s56, s6
	global_load_lds_dwordx4 v[4:5], off
	v_add_u32_e32 v4, 0x2000, v66
	s_addc_u32 s7, s57, s7
	v_readfirstlane_b32 s29, v4
	v_add_u32_e32 v6, 0x3000, v66
	v_lshl_add_u64 v[2:3], s[6:7], 0, v[64:65]
	s_mov_b32 m0, s29
	v_readfirstlane_b32 s29, v6
	v_add_u32_e32 v9, 0x4000, v66
	global_load_lds_dwordx4 v[2:3], off
	v_lshl_add_u64 v[4:5], v[2:3], 0, s[26:27]
	s_mov_b32 m0, s29
	s_mov_b64 s[34:35], 0x10000
	v_readfirstlane_b32 s29, v9
	global_load_lds_dwordx4 v[4:5], off
	v_lshl_add_u64 v[4:5], v[0:1], 0, s[34:35]
	s_mov_b32 m0, s29
	s_mov_b64 s[34:35], 0x120000
	global_load_lds_dwordx4 v[4:5], off
	v_add_u32_e32 v4, 0x5000, v66
	v_lshl_add_u64 v[6:7], v[2:3], 0, s[34:35]
	s_mov_b64 s[34:35], 0x11000
	v_readfirstlane_b32 s29, v4
	v_lshl_add_u64 v[0:1], v[0:1], 0, s[34:35]
	s_mov_b32 m0, s29
	s_mov_b64 s[34:35], 0x121000
	global_load_lds_dwordx4 v[0:1], off
	v_add_u32_e32 v0, 0x6000, v66
	s_nop 0
	v_readfirstlane_b32 s29, v0
	v_lshl_add_u64 v[0:1], v[2:3], 0, s[34:35]
	v_add_u32_e32 v2, 0x7000, v66
	s_mov_b32 m0, s29
	v_readfirstlane_b32 s29, v2
	global_load_lds_dwordx4 v[6:7], off
	s_mov_b32 m0, s29
	v_bfe_u32 v2, v8, 2, 2
	global_load_lds_dwordx4 v[0:1], off
	v_bfe_u32 v0, v8, 5, 1
	v_lshrrev_b32_e32 v1, 2, v8
	v_lshlrev_b32_e32 v3, 6, v8
	v_bitop3_b32 v1, v0, v1, 3 bitop3:0x78
	v_bitop3_b32 v0, v0, v2, 2 bitop3:0x36
	v_and_b32_e32 v2, 0x7c0, v3
	v_lshl_or_b32 v67, v0, 4, v2
	v_lshlrev_b32_e32 v0, 5, v8
	v_and_b32_e32 v69, 0xfffff000, v0
	v_mov_b32_e32 v0, 0
	v_lshl_or_b32 v68, v1, 4, v2
	v_and_b32_e32 v70, 0x1000, v3
	s_mov_b32 s29, 15
	s_mov_b32 s34, 0
	v_mov_b32_e32 v1, v0
	v_mov_b32_e32 v2, v0
	v_mov_b32_e32 v3, v0
	v_mov_b32_e32 v4, v0
	v_mov_b32_e32 v5, v0
	v_mov_b32_e32 v6, v0
	v_mov_b32_e32 v7, v0
	v_mov_b32_e32 v8, v0
	v_mov_b32_e32 v9, v0
	v_mov_b32_e32 v10, v0
	v_mov_b32_e32 v11, v0
	v_mov_b32_e32 v12, v0
	v_mov_b32_e32 v13, v0
	v_mov_b32_e32 v14, v0
	v_mov_b32_e32 v15, v0
	v_mov_b32_e32 v16, v0
	v_mov_b32_e32 v17, v0
	v_mov_b32_e32 v18, v0
	v_mov_b32_e32 v19, v0
	v_mov_b32_e32 v20, v0
	v_mov_b32_e32 v21, v0
	v_mov_b32_e32 v22, v0
	v_mov_b32_e32 v23, v0
	v_mov_b32_e32 v24, v0
	v_mov_b32_e32 v25, v0
	v_mov_b32_e32 v26, v0
	v_mov_b32_e32 v27, v0
	v_mov_b32_e32 v28, v0
	v_mov_b32_e32 v29, v0
	v_mov_b32_e32 v30, v0
	v_mov_b32_e32 v31, v0
	v_mov_b32_e32 v32, v0
	v_mov_b32_e32 v33, v0
	v_mov_b32_e32 v34, v0
	v_mov_b32_e32 v35, v0
	v_mov_b32_e32 v36, v0
	v_mov_b32_e32 v37, v0
	v_mov_b32_e32 v38, v0
	v_mov_b32_e32 v39, v0
	v_mov_b32_e32 v40, v0
	v_mov_b32_e32 v41, v0
	v_mov_b32_e32 v42, v0
	v_mov_b32_e32 v43, v0
	v_mov_b32_e32 v44, v0
	v_mov_b32_e32 v45, v0
	v_mov_b32_e32 v46, v0
	v_mov_b32_e32 v47, v0
	v_mov_b32_e32 v48, v0
	v_mov_b32_e32 v49, v0
	v_mov_b32_e32 v50, v0
	v_mov_b32_e32 v51, v0
	v_mov_b32_e32 v52, v0
	v_mov_b32_e32 v53, v0
	v_mov_b32_e32 v54, v0
	v_mov_b32_e32 v55, v0
	v_mov_b32_e32 v56, v0
	v_mov_b32_e32 v57, v0
	v_mov_b32_e32 v58, v0
	v_mov_b32_e32 v59, v0
	v_mov_b32_e32 v60, v0
	v_mov_b32_e32 v61, v0
	v_mov_b32_e32 v62, v0
	v_mov_b32_e32 v63, v0
	v_readfirstlane_b32 s100, v66
	v_add_u32_e32 v101, 0x1000, v64
	v_add_u32_e32 v106, v70, v68
	v_add_u32_e32 v107, v69, v68
	v_add_u32_e32 v108, v70, v67
	v_add_u32_e32 v109, v69, v67
	s_add_u32 s4, s4, 0x20000
	s_addc_u32 s5, s5, 0
	s_add_u32 s6, s6, 0x240000
	s_addc_u32 s7, s7, 0
	s_add_i32 s101, s100, 0x8000
	s_mov_b32 m0, s101
	s_nop 0
	global_load_lds_dwordx4 v64, s[4:5]
	s_add_u32 m0, s101, 0x1000
	s_nop 0
	global_load_lds_dwordx4 v101, s[4:5]
	s_add_u32 m0, s101, 0x2000
	s_nop 0
	global_load_lds_dwordx4 v64, s[6:7]
	s_add_u32 m0, s101, 0x3000
	s_nop 0
	global_load_lds_dwordx4 v101, s[6:7]
	s_add_u32 s4, s4, 0x10000
	s_addc_u32 s5, s5, 0
	s_add_u32 s6, s6, 0x120000
	s_addc_u32 s7, s7, 0
	s_mov_b32 s34, 0
	s_mov_b32 s29, 28
	s_lshl_b32 s35, s34, 14
	s_add_i32 s35, s35, 32
	v_add_u32_e32 v110, s35, v106
	v_add_u32_e32 v111, s35, v107
	v_add_u32_e32 v112, s35, v108
	v_add_u32_e32 v113, s35, v109
	s_waitcnt vmcnt(8)
	s_waitcnt lgkmcnt(0)
	s_barrier
	ds_read_b128 v[72:75], v110
	ds_read_b128 v[76:79], v110 offset:2048
	ds_read_b128 v[80:83], v111 offset:8192
	ds_read_b128 v[84:87], v111 offset:10240
	s_add_i32 s35, s34, 3
	s_and_b32 s35, s35, 3
	s_lshl_b32 s35, s35, 14
	s_add_i32 s101, s35, s100
	s_mov_b32 m0, s101
	s_add_i32 s34, s34, 1
	s_and_b32 s34, s34, 3
	s_nop 0
	global_load_lds_dwordx4 v64, s[4:5]
	s_add_u32 m0, s101, 0x1000
	s_nop 0
	global_load_lds_dwordx4 v101, s[4:5]
	s_add_u32 m0, s101, 0x2000
	s_nop 0
	global_load_lds_dwordx4 v64, s[6:7]
	s_add_u32 m0, s101, 0x3000
	s_nop 0
	global_load_lds_dwordx4 v101, s[6:7]
	s_add_u32 s4, s4, 0x10000
	s_addc_u32 s5, s5, 0
	s_add_u32 s6, s6, 0x120000
	s_addc_u32 s7, s7, 0
	s_waitcnt lgkmcnt(0)
	v_mfma_f32_32x32x16_bf16 v[48:63], v[72:75], v[80:83], v[48:63]
	ds_read_b128 v[120:123], v112
	v_mfma_f32_32x32x16_bf16 v[32:47], v[72:75], v[84:87], v[32:47]
	ds_read_b128 v[128:131], v113 offset:8192
	v_mfma_f32_32x32x16_bf16 v[16:31], v[76:79], v[80:83], v[16:31]
	ds_read_b128 v[124:127], v112 offset:2048
	v_mfma_f32_32x32x16_bf16 v[0:15], v[76:79], v[84:87], v[0:15]
	ds_read_b128 v[132:135], v113 offset:10240
; template <bool VMODE, int TJ>
; DI void gemm_mainloop(const bf16_t* __restrict__ W, const bf16_t* __restrict__ X, int NW, char* smem, f32x16 (&acc)[2][TJ]) {
;     ...
;         for (int kp = 0; kp < 16; ++kp) {
;             if (TJ == 1 && kp + 1 < 16) asm volatile("s_waitcnt vmcnt(6)" ::: "memory");
;             else asm volatile("s_waitcnt vmcnt(0)" ::: "memory");
;             __builtin_amdgcn_s_barrier();
;             const int sn2 = (TJ == 1) ? ((sl + 4 >= NSL) ? sl + 4 - NSL : sl + 4) : 2 - sl;
;             {
;                 const char* sw = smem + sl * STAGE + wf * 64 * 64;
;                 const char* sx = smem + sl * STAGE + 8192 + wt * (32 * TJ) * 64;
;                 bf16x8 fw[2], fx[TJ];
; #pragma unroll
;                 for (int i = 0; i < 2; ++i) fw[i] = *(const bf16x8*)(sw + i * 32 * 64 + fo0);
; #pragma unroll
;                 for (int j = 0; j < TJ; ++j) fx[j] = *(const bf16x8*)(sx + j * 32 * 64 + fo0);
;                 __builtin_amdgcn_sched_barrier(0);
;                 if (TJ == 1) { if (kp + 2 < 16) { G_ISSUE(2 * kp + 4, sn2); G_ISSUE(2 * kp + 5, sn2 + 1); } }
;                 else if (kp + 1 < 16) { G_ISSUE(2 * kp + 2, sn2); G_ISSUE(2 * kp + 3, sn2 + 1); }
;                 __builtin_amdgcn_sched_barrier(0);
; #pragma unroll
;                 for (int i = 0; i < 2; ++i)
; #pragma unroll
;                     for (int j = 0; j < TJ; ++j) acc[i][j] = VMODE ? MFMA(fx[j], fw[i], acc[i][j]) : MFMA(fw[i], fx[j], acc[i][j]);
; #pragma unroll
;                 for (int i = 0; i < 2; ++i) fw[i] = *(const bf16x8*)(sw + i * 32 * 64 + fo1);
; #pragma unroll
;                 for (int j = 0; j < TJ; ++j) fx[j] = *(const bf16x8*)(sx + j * 32 * 64 + fo1);
; #pragma unroll
;                 for (int i = 0; i < 2; ++i)
; #pragma unroll
;                     for (int j = 0; j < TJ; ++j) acc[i][j] = VMODE ? MFMA(fx[j], fw[i], acc[i][j]) : MFMA(fw[i], fx[j], acc[i][j]);
;             }
;             G_COMPUTE(sl + 1);
;             sl = (sl + 2 >= NSL) ? 0 : sl + 2;
;         }
; template <int TJ>
; DI void outproj_tile(const Params& p, int l, char* smem, int b, int trow0, int n0) {
;     ...
;     const float* gt = p.mod + ((size_t)l * 9 + (trow0 < SEQ ? b : 8)) * 3072 + 2048 + n0 + 64 * wf;
;     const float* xs = src_row(p, l, b, trow0 + 32 * TJ * wt) + n0 + 64 * wf;
;     float* xd = dst_row(p, b, trow0 + 32 * TJ * wt) + n0 + 64 * wf;
.Lopx_loop:
	s_lshl_b32 s35, s34, 14
	s_add_i32 s35, s35, 32
	v_add_u32_e32 v110, s35, v106
	v_add_u32_e32 v111, s35, v107
	v_add_u32_e32 v112, s35, v108
	v_add_u32_e32 v113, s35, v109
	s_waitcnt vmcnt(8)
	s_waitcnt lgkmcnt(0)
	s_barrier
	ds_read_b128 v[72:75], v110
	ds_read_b128 v[76:79], v110 offset:2048
	ds_read_b128 v[80:83], v111 offset:8192
	ds_read_b128 v[84:87], v111 offset:10240
	s_add_i32 s35, s34, 3
	s_and_b32 s35, s35, 3
	s_lshl_b32 s35, s35, 14
	s_add_i32 s101, s35, s100
	s_mov_b32 m0, s101
	s_add_i32 s34, s34, 1
	s_and_b32 s34, s34, 3
	v_mfma_f32_32x32x16_bf16 v[48:63], v[120:123], v[128:131], v[48:63]
	global_load_lds_dwordx4 v64, s[4:5]
	s_add_u32 m0, s101, 0x1000
	v_mfma_f32_32x32x16_bf16 v[32:47], v[120:123], v[132:135], v[32:47]
	global_load_lds_dwordx4 v101, s[4:5]
	s_add_u32 m0, s101, 0x2000
	v_mfma_f32_32x32x16_bf16 v[16:31], v[124:127], v[128:131], v[16:31]
	global_load_lds_dwordx4 v64, s[6:7]
	s_add_u32 m0, s101, 0x3000
	v_mfma_f32_32x32x16_bf16 v[0:15], v[124:127], v[132:135], v[0:15]
	global_load_lds_dwordx4 v101, s[6:7]
	s_add_u32 s4, s4, 0x10000
	s_addc_u32 s5, s5, 0
	s_add_u32 s6, s6, 0x120000
	s_addc_u32 s7, s7, 0
	s_waitcnt lgkmcnt(0)
	v_mfma_f32_32x32x16_bf16 v[48:63], v[72:75], v[80:83], v[48:63]
	ds_read_b128 v[120:123], v112
	v_mfma_f32_32x32x16_bf16 v[32:47], v[72:75], v[84:87], v[32:47]
	ds_read_b128 v[128:131], v113 offset:8192
	v_mfma_f32_32x32x16_bf16 v[16:31], v[76:79], v[80:83], v[16:31]
	ds_read_b128 v[124:127], v112 offset:2048
	v_mfma_f32_32x32x16_bf16 v[0:15], v[76:79], v[84:87], v[0:15]
	ds_read_b128 v[132:135], v113 offset:10240
	s_add_i32 s29, s29, -1
	s_cmp_lg_u32 s29, 0
	s_cbranch_scc1 .Lopx_loop
	s_lshl_b32 s35, s34, 14
	s_add_i32 s35, s35, 32
	v_add_u32_e32 v110, s35, v106
	v_add_u32_e32 v111, s35, v107
	v_add_u32_e32 v112, s35, v108
	v_add_u32_e32 v113, s35, v109
	s_waitcnt vmcnt(8)
	s_waitcnt lgkmcnt(0)
	s_barrier
	ds_read_b128 v[72:75], v110
	ds_read_b128 v[76:79], v110 offset:2048
	ds_read_b128 v[80:83], v111 offset:8192
	ds_read_b128 v[84:87], v111 offset:10240
	s_add_i32 s34, s34, 1
	s_and_b32 s34, s34, 3
	v_mfma_f32_32x32x16_bf16 v[48:63], v[120:123], v[128:131], v[48:63]
	v_mfma_f32_32x32x16_bf16 v[32:47], v[120:123], v[132:135], v[32:47]
	v_mfma_f32_32x32x16_bf16 v[16:31], v[124:127], v[128:131], v[16:31]
	v_mfma_f32_32x32x16_bf16 v[0:15], v[124:127], v[132:135], v[0:15]
	s_waitcnt lgkmcnt(0)
	v_mfma_f32_32x32x16_bf16 v[48:63], v[72:75], v[80:83], v[48:63]
	ds_read_b128 v[120:123], v112
	v_mfma_f32_32x32x16_bf16 v[32:47], v[72:75], v[84:87], v[32:47]
	ds_read_b128 v[128:131], v113 offset:8192
	v_mfma_f32_32x32x16_bf16 v[16:31], v[76:79], v[80:83], v[16:31]
	ds_read_b128 v[124:127], v112 offset:2048
	v_mfma_f32_32x32x16_bf16 v[0:15], v[76:79], v[84:87], v[0:15]
	ds_read_b128 v[132:135], v113 offset:10240
	s_lshl_b32 s35, s34, 14
	s_add_i32 s35, s35, 32
	v_add_u32_e32 v110, s35, v106
	v_add_u32_e32 v111, s35, v107
	v_add_u32_e32 v112, s35, v108
	v_add_u32_e32 v113, s35, v109
	s_waitcnt vmcnt(4)
	s_waitcnt lgkmcnt(0)
	s_barrier
	ds_read_b128 v[72:75], v110
	ds_read_b128 v[76:79], v110 offset:2048
	ds_read_b128 v[80:83], v111 offset:8192
	ds_read_b128 v[84:87], v111 offset:10240
	s_add_i32 s34, s34, 1
	s_and_b32 s34, s34, 3
	v_mfma_f32_32x32x16_bf16 v[48:63], v[120:123], v[128:131], v[48:63]
	v_mfma_f32_32x32x16_bf16 v[32:47], v[120:123], v[132:135], v[32:47]
	v_mfma_f32_32x32x16_bf16 v[16:31], v[124:127], v[128:131], v[16:31]
	v_mfma_f32_32x32x16_bf16 v[0:15], v[124:127], v[132:135], v[0:15]
	s_waitcnt lgkmcnt(0)
	v_mfma_f32_32x32x16_bf16 v[48:63], v[72:75], v[80:83], v[48:63]
	ds_read_b128 v[120:123], v112
	v_mfma_f32_32x32x16_bf16 v[32:47], v[72:75], v[84:87], v[32:47]
	ds_read_b128 v[128:131], v113 offset:8192
	v_mfma_f32_32x32x16_bf16 v[16:31], v[76:79], v[80:83], v[16:31]
	ds_read_b128 v[124:127], v112 offset:2048
	v_mfma_f32_32x32x16_bf16 v[0:15], v[76:79], v[84:87], v[0:15]
	ds_read_b128 v[132:135], v113 offset:10240
	s_lshl_b32 s35, s34, 14
	s_add_i32 s35, s35, 32
	v_add_u32_e32 v110, s35, v106
	v_add_u32_e32 v111, s35, v107
	v_add_u32_e32 v112, s35, v108
	v_add_u32_e32 v113, s35, v109
	s_waitcnt vmcnt(0)
	s_waitcnt lgkmcnt(0)
	s_barrier
	ds_read_b128 v[72:75], v110
	ds_read_b128 v[76:79], v110 offset:2048
	ds_read_b128 v[80:83], v111 offset:8192
	ds_read_b128 v[84:87], v111 offset:10240
	s_add_i32 s34, s34, 1
	s_and_b32 s34, s34, 3
	v_mfma_f32_32x32x16_bf16 v[48:63], v[120:123], v[128:131], v[48:63]
	v_mfma_f32_32x32x16_bf16 v[32:47], v[120:123], v[132:135], v[32:47]
	v_mfma_f32_32x32x16_bf16 v[16:31], v[124:127], v[128:131], v[16:31]
	v_mfma_f32_32x32x16_bf16 v[0:15], v[124:127], v[132:135], v[0:15]
	s_waitcnt lgkmcnt(0)
	v_mfma_f32_32x32x16_bf16 v[48:63], v[72:75], v[80:83], v[48:63]
	ds_read_b128 v[120:123], v112
	v_mfma_f32_32x32x16_bf16 v[32:47], v[72:75], v[84:87], v[32:47]
	ds_read_b128 v[128:131], v113 offset:8192
	v_mfma_f32_32x32x16_bf16 v[16:31], v[76:79], v[80:83], v[16:31]
	ds_read_b128 v[124:127], v112 offset:2048
	v_mfma_f32_32x32x16_bf16 v[0:15], v[76:79], v[84:87], v[0:15]
	ds_read_b128 v[132:135], v113 offset:10240
	s_waitcnt lgkmcnt(0)
	v_mfma_f32_32x32x16_bf16 v[48:63], v[120:123], v[128:131], v[48:63]
	v_mfma_f32_32x32x16_bf16 v[32:47], v[120:123], v[132:135], v[32:47]
	s_waitcnt vmcnt(0) lgkmcnt(0)
	s_barrier
	s_mov_b64 s[4:5], -1
	s_and_b64 vcc, exec, s[50:51]
	s_load_dwordx2 s[52:53], s[0:1], 0xe0
	v_mfma_f32_32x32x16_bf16 v[16:31], v[124:127], v[128:131], v[16:31]
	v_mfma_f32_32x32x16_bf16 v[0:15], v[124:127], v[132:135], v[0:15]
	v_ashrrev_i32_e32 v64, 1, v116
	v_and_b32_e32 v64, 0xffffffc0, v64
	v_add_u32_e32 v66, s28, v64
	v_cmp_gt_i32_e64 s[40:41], s61, v66
	v_cmp_lt_i32_e64 s[42:43], s21, v66
	s_cbranch_vccz .LBB0_47
	s_and_saveexec_b64 s[4:5], s[42:43]
	s_xor_b64 s[4:5], exec, s[4:5]
	v_add_u32_e32 v192, 0xfffff800, v66
	v_mov_b64_e32 v[68:69], v[192:193]
	s_or_saveexec_b64 s[4:5], s[4:5]
	v_readlane_b32 s6, v254, 7
	v_readlane_b32 s7, v254, 8
	s_nop 1
	v_mov_b64_e32 v[64:65], s[6:7]
	v_readlane_b32 s6, v255, 19
	v_readlane_b32 s7, v255, 20
	s_nop 1
	v_mov_b64_e32 v[70:71], s[6:7]
	s_xor_b64 exec, exec, s[4:5]
	s_cbranch_execz .LBB0_46
	v_readlane_b32 s6, v254, 9
	v_readlane_b32 s7, v254, 10
	v_ashrrev_i32_e32 v67, 31, v66
	v_mov_b64_e32 v[68:69], v[66:67]
	v_mov_b64_e32 v[64:65], s[6:7]
	v_readlane_b32 s6, v255, 21
	v_readlane_b32 s7, v255, 22
	s_nop 1
	v_mov_b64_e32 v[70:71], s[6:7]
